# refined nt loads, additionally LN2 gain/bias vector loads (reused) no longer nt
# speedup vs baseline: 1.0012x; 1.0012x over previous
; DI void phase_ln(const void* srcv, const int srcmode, const bf16_t* xres,
;                  const float* g, const float* b, float* dstf, bf16_t* dstb, int ntok, int tid,
;                  unsigned char* smem, const float* wg, const float* bias16, float* gpre) {
;     ...
;     f32x4 gvv[2][2], bvv[2][2];
; #pragma unroll
;     for (int q = 0; q < 2; ++q)
; #pragma unroll
;         for (int h = 0; h < 2; ++h) { gvv[q][h] = *(const f32x4*)(g + q * 512 + lane * 8 + h * 4); bvv[q][h] = *(const f32x4*)(b + q * 512 + lane * 8 + h * 4); }
;     u32x4 na[2], nb[2];
;     ...
;     {
;         const int r0 = blockIdx.x * 8 + wid;
;         if (r0 < ntok) LN_LOAD(r0);
;     }
.LBB0_151:
	s_and_saveexec_b64 s[46:47], s[36:37]
	s_cbranch_execz .LBB0_150
	s_mov_b32 s13, s67
	s_xor_b64 s[48:49], s[20:21], -1
	v_readlane_b32 s52, v253, 3
	s_and_b64 s[30:31], s[20:21], exec
	v_readlane_b32 s56, v253, 7
	v_readlane_b32 s57, v253, 8
	v_readlane_b32 s58, v253, 9
	v_readlane_b32 s59, v253, 10
	s_cselect_b32 s31, s26, s57
	s_cselect_b32 s30, s23, s56
	s_cselect_b32 s35, s28, s59
	s_cselect_b32 s34, s27, s58
	global_load_dwordx4 v[2:5], v80, s[30:31] offset:16
	global_load_dwordx4 v[6:9], v80, s[30:31]
	global_load_dwordx4 v[10:13], v80, s[34:35] offset:16
	global_load_dwordx4 v[14:17], v80, s[34:35]
	global_load_dwordx4 v[18:21], v80, s[30:31] offset:2064
	global_load_dwordx4 v[22:25], v80, s[30:31] offset:2048
	global_load_dwordx4 v[26:29], v80, s[34:35] offset:2064
	global_load_dwordx4 v[30:33], v80, s[34:35] offset:2048
	v_readlane_b32 s30, v255, 7
	v_readlane_b32 s31, v255, 8
	s_cselect_b32 s39, s31, s8
	s_cselect_b32 s38, s30, s9
	s_waitcnt vmcnt(9)
	v_lshl_add_u64 v[40:41], v[60:61], 1, s[38:39]
	v_mov_b32_e32 v81, v1
	v_lshl_add_u64 v[34:35], v[40:41], 0, v[62:63]
	s_waitcnt vmcnt(8)
	v_lshl_add_u64 v[46:47], v[34:35], 0, v[80:81]
	s_mov_b64 s[40:41], -1
	s_and_b64 vcc, exec, s[48:49]
	v_readlane_b32 s53, v253, 4
	v_readlane_b32 s54, v253, 5
	v_readlane_b32 s55, v253, 6
	v_readlane_b32 s60, v253, 11
	v_readlane_b32 s61, v253, 12
	v_readlane_b32 s62, v253, 13
	v_readlane_b32 s63, v253, 14
	v_readlane_b32 s64, v253, 15
	v_readlane_b32 s65, v253, 16
	v_readlane_b32 s66, v253, 17
	v_readlane_b32 s67, v253, 18
	s_cbranch_vccz .LBB0_154
	global_load_dwordx4 v[34:37], v[46:47], off nt
	v_lshl_add_u64 v[38:39], v[46:47], 0, 16
	s_mov_b64 s[40:41], 0
